# INIT_ACC prologues (w_out, down): the wait in front of the bf16 residual unpack counts only the 16 residual loads (vmcnt(8)), the tile-0 LDS-DMA loads stay in flight during the unpack; on top of the K
# speedup vs baseline: 1.0033x; 1.0033x over previous
.LBB0_1573:
	s_waitcnt vmcnt(8)
	v_lshlrev_b32_e32 v90, 16, v48
	v_and_b32_e32 v91, 0xffff0000, v48
	v_lshlrev_b32_e32 v92, 16, v49
	v_and_b32_e32 v93, 0xffff0000, v49
	v_lshlrev_b32_e32 v94, 16, v46
	v_and_b32_e32 v95, 0xffff0000, v46
	v_lshlrev_b32_e32 v96, 16, v47
	v_and_b32_e32 v97, 0xffff0000, v47
	v_lshlrev_b32_e32 v46, 16, v28
	v_and_b32_e32 v47, 0xffff0000, v28
	v_lshlrev_b32_e32 v48, 16, v29
	v_and_b32_e32 v49, 0xffff0000, v29
	s_add_i32 m0, s56, 0x18000
	v_lshl_add_u64 v[28:29], v[144:145], 0, s[16:17]
	s_lshl_b32 s31, s28, 13
	s_lshl_b32 s34, s21, 7
	s_waitcnt vmcnt(2)
	s_barrier
	global_load_lds_dwordx4 v[28:29], off
	v_lshl_add_u64 v[28:29], v[142:143], 0, s[16:17]
	s_add_i32 m0, s56, 0x1a000
	s_add_i32 s60, s56, 0x8000
	s_add_i32 s61, s56, 0xa000
	global_load_lds_dwordx4 v[28:29], off
	v_lshl_add_u64 v[28:29], v[68:69], 0, s[16:17]
	s_mov_b32 m0, s60
	s_add_u32 s28, s46, 0x80080
	global_load_lds_dwordx4 v[28:29], off
	v_lshl_add_u64 v[28:29], v[140:141], 0, s[16:17]
	s_mov_b32 m0, s61
	s_addc_u32 s29, s47, 0
	global_load_lds_dwordx4 v[28:29], off
	s_add_i32 m0, s56, 0x1c000
	v_lshl_add_u64 v[28:29], s[28:29], 0, v[134:135]
	global_load_lds_dwordx4 v[28:29], off
	v_lshl_add_u64 v[28:29], s[28:29], 0, v[138:139]
	s_add_i32 m0, s56, 0x1e000
	v_or_b32_e32 v151, s9, v150
	global_load_lds_dwordx4 v[28:29], off
	v_lshlrev_b32_e32 v140, 6, v151
	s_movk_i32 s28, 0x3c0
	v_lshlrev_b32_e32 v141, 2, v151
	v_and_or_b32 v140, v140, s28, v180
	v_and_b32_e32 v141, 32, v141
	v_bitop3_b32 v144, v140, s31, v141 bitop3:0xde
	v_lshlrev_b32_e32 v141, 2, v150
	v_lshl_or_b32 v140, v150, 6, v180
	v_and_b32_e32 v141, 32, v141
	v_bitop3_b32 v152, v140, s34, v141 bitop3:0xde
	v_lshlrev_b32_e32 v140, 15, v146
	v_lshlrev_b32_e32 v142, 15, v154
	v_and_b32_e32 v140, 0xffff0000, v140
	v_and_b32_e32 v142, 0xffff0000, v142
	s_waitcnt vmcnt(6)
	v_lshl_add_u32 v140, v147, 12, v140
	v_and_b32_e32 v141, 1, v146
	v_lshl_add_u32 v142, v155, 12, v142
	v_and_b32_e32 v143, 1, v154
	v_lshlrev_b32_e32 v157, 3, v131
	s_cmpk_lt_u32 s30, 0x100
	v_lshl_or_b32 v140, v141, 6, v140
	v_lshl_or_b32 v142, v143, 6, v142
	v_lshlrev_b32_e32 v126, 16, v64
	v_and_b32_e32 v127, 0xffff0000, v64
	v_lshlrev_b32_e32 v128, 16, v65
	v_and_b32_e32 v129, 0xffff0000, v65
	v_lshlrev_b32_e32 v114, 16, v66
	v_and_b32_e32 v115, 0xffff0000, v66
	v_lshlrev_b32_e32 v116, 16, v67
	v_and_b32_e32 v117, 0xffff0000, v67
	v_lshlrev_b32_e32 v118, 16, v60
	v_and_b32_e32 v119, 0xffff0000, v60
	v_lshlrev_b32_e32 v120, 16, v61
	v_and_b32_e32 v121, 0xffff0000, v61
	v_lshlrev_b32_e32 v122, 16, v62
	v_and_b32_e32 v123, 0xffff0000, v62
	v_lshlrev_b32_e32 v124, 16, v63
	v_and_b32_e32 v125, 0xffff0000, v63
	v_lshlrev_b32_e32 v106, 16, v56
	v_and_b32_e32 v107, 0xffff0000, v56
	v_lshlrev_b32_e32 v108, 16, v57
	v_and_b32_e32 v109, 0xffff0000, v57
	v_lshlrev_b32_e32 v98, 16, v58
	v_and_b32_e32 v99, 0xffff0000, v58
	v_lshlrev_b32_e32 v100, 16, v59
	v_and_b32_e32 v101, 0xffff0000, v59
	v_lshlrev_b32_e32 v102, 16, v52
	v_and_b32_e32 v103, 0xffff0000, v52
	v_lshlrev_b32_e32 v104, 16, v53
	v_and_b32_e32 v105, 0xffff0000, v53
	v_lshlrev_b32_e32 v110, 16, v54
	v_and_b32_e32 v111, 0xffff0000, v54
	v_lshlrev_b32_e32 v112, 16, v55
	v_and_b32_e32 v113, 0xffff0000, v55
	v_lshlrev_b32_e32 v82, 16, v50
	v_and_b32_e32 v83, 0xffff0000, v50
	v_lshlrev_b32_e32 v84, 16, v51
	v_and_b32_e32 v85, 0xffff0000, v51
	v_lshlrev_b32_e32 v86, 16, v44
	v_and_b32_e32 v87, 0xffff0000, v44
	v_lshlrev_b32_e32 v88, 16, v45
	v_and_b32_e32 v89, 0xffff0000, v45
	v_lshlrev_b32_e32 v74, 16, v40
	v_and_b32_e32 v75, 0xffff0000, v40
	v_lshlrev_b32_e32 v76, 16, v41
	v_and_b32_e32 v77, 0xffff0000, v41
	v_lshlrev_b32_e32 v54, 16, v42
	v_and_b32_e32 v55, 0xffff0000, v42
	v_lshlrev_b32_e32 v56, 16, v43
	v_and_b32_e32 v57, 0xffff0000, v43
	v_lshlrev_b32_e32 v70, 16, v36
	v_and_b32_e32 v71, 0xffff0000, v36
	v_lshlrev_b32_e32 v72, 16, v37
	v_and_b32_e32 v73, 0xffff0000, v37
	v_lshlrev_b32_e32 v78, 16, v38
	v_and_b32_e32 v79, 0xffff0000, v38
	v_lshlrev_b32_e32 v80, 16, v39
	v_and_b32_e32 v81, 0xffff0000, v39
	v_lshlrev_b32_e32 v50, 16, v32
	v_and_b32_e32 v51, 0xffff0000, v32
	v_lshlrev_b32_e32 v52, 16, v33
	v_and_b32_e32 v53, 0xffff0000, v33
	v_lshlrev_b32_e32 v38, 16, v34
	v_and_b32_e32 v39, 0xffff0000, v34
	v_lshlrev_b32_e32 v40, 16, v35
	v_and_b32_e32 v41, 0xffff0000, v35
	v_lshlrev_b32_e32 v58, 16, v30
	v_and_b32_e32 v59, 0xffff0000, v30
	v_lshlrev_b32_e32 v60, 16, v31
	v_and_b32_e32 v61, 0xffff0000, v31
	v_lshlrev_b32_e32 v22, 16, v24
	v_and_b32_e32 v23, 0xffff0000, v24
	v_lshlrev_b32_e32 v24, 16, v25
	v_and_b32_e32 v25, 0xffff0000, v25
	v_lshlrev_b32_e32 v42, 16, v26
	v_and_b32_e32 v43, 0xffff0000, v26
	v_lshlrev_b32_e32 v44, 16, v27
	v_and_b32_e32 v45, 0xffff0000, v27
	v_lshlrev_b32_e32 v62, 16, v18
	v_and_b32_e32 v63, 0xffff0000, v18
	v_lshlrev_b32_e32 v64, 16, v19
	v_and_b32_e32 v65, 0xffff0000, v19
	v_lshlrev_b32_e32 v66, 16, v20
	v_and_b32_e32 v67, 0xffff0000, v20
	v_lshlrev_b32_e32 v68, 16, v21
	v_and_b32_e32 v69, 0xffff0000, v21
	v_lshlrev_b32_e32 v30, 16, v10
	v_and_b32_e32 v31, 0xffff0000, v10
	v_lshlrev_b32_e32 v32, 16, v11
	v_and_b32_e32 v33, 0xffff0000, v11
	v_lshlrev_b32_e32 v18, 16, v12
	v_and_b32_e32 v19, 0xffff0000, v12
	v_lshlrev_b32_e32 v20, 16, v13
	v_and_b32_e32 v21, 0xffff0000, v13
	v_lshlrev_b32_e32 v26, 16, v6
	v_and_b32_e32 v27, 0xffff0000, v6
	v_lshlrev_b32_e32 v28, 16, v7
	v_and_b32_e32 v29, 0xffff0000, v7
	v_lshlrev_b32_e32 v34, 16, v8
	v_and_b32_e32 v35, 0xffff0000, v8
	v_lshlrev_b32_e32 v36, 16, v9
	v_and_b32_e32 v37, 0xffff0000, v9
	v_lshlrev_b32_e32 v10, 16, v2
	v_and_b32_e32 v11, 0xffff0000, v2
	v_lshlrev_b32_e32 v12, 16, v3
	v_and_b32_e32 v13, 0xffff0000, v3
	v_lshlrev_b32_e32 v2, 16, v4
	v_and_b32_e32 v3, 0xffff0000, v4
	v_lshlrev_b32_e32 v4, 16, v5
	v_and_b32_e32 v5, 0xffff0000, v5
	v_lshlrev_b32_e32 v6, 16, v14
	v_and_b32_e32 v7, 0xffff0000, v14
	v_lshlrev_b32_e32 v8, 16, v15
	v_and_b32_e32 v9, 0xffff0000, v15
	v_lshlrev_b32_e32 v14, 16, v16
	v_and_b32_e32 v15, 0xffff0000, v16
	v_lshlrev_b32_e32 v16, 16, v17
	v_and_b32_e32 v17, 0xffff0000, v17
	s_cselect_b64 s[28:29], -1, 0
	s_ashr_i32 s62, s7, 31
	v_lshl_add_u32 v140, v153, 1, v140
	v_mov_b32_e32 v141, v181
	v_lshl_add_u32 v142, v156, 1, v142
	v_mov_b32_e32 v143, v181
	s_mov_b32 s63, 0
	v_add_u32_e32 v153, 0, v144
	v_lshlrev_b32_e32 v180, 1, v157
	s_barrier
	s_branch .LBB0_1576

.LBB0_2227:
	s_waitcnt vmcnt(8)
	v_lshlrev_b32_e32 v90, 16, v48
	v_and_b32_e32 v91, 0xffff0000, v48
	v_lshlrev_b32_e32 v92, 16, v49
	v_and_b32_e32 v93, 0xffff0000, v49
	v_lshlrev_b32_e32 v94, 16, v46
	v_and_b32_e32 v95, 0xffff0000, v46
	v_lshlrev_b32_e32 v96, 16, v47
	v_and_b32_e32 v97, 0xffff0000, v47
	v_lshlrev_b32_e32 v46, 16, v28
	v_and_b32_e32 v47, 0xffff0000, v28
	v_lshlrev_b32_e32 v48, 16, v29
	v_and_b32_e32 v49, 0xffff0000, v29
	s_add_i32 m0, s43, 0x18000
	v_lshl_add_u64 v[28:29], v[146:147], 0, s[16:17]
	s_lshl_b32 s23, s18, 13
	s_lshl_b32 s24, s42, 7
	s_waitcnt vmcnt(2)
	s_barrier
	global_load_lds_dwordx4 v[28:29], off
	v_lshl_add_u64 v[28:29], v[144:145], 0, s[16:17]
	s_add_i32 m0, s43, 0x1a000
	s_add_i32 s48, s43, 0x8000
	s_add_i32 s49, s43, 0xa000
	global_load_lds_dwordx4 v[28:29], off
	v_lshl_add_u64 v[28:29], v[68:69], 0, s[16:17]
	s_mov_b32 m0, s48
	s_add_u32 s18, s28, 0x158080
	global_load_lds_dwordx4 v[28:29], off
	v_lshl_add_u64 v[28:29], v[142:143], 0, s[16:17]
	s_mov_b32 m0, s49
	s_addc_u32 s19, s29, 0
	global_load_lds_dwordx4 v[28:29], off
	s_add_i32 m0, s43, 0x1c000
	v_lshl_add_u64 v[28:29], s[18:19], 0, v[136:137]
	global_load_lds_dwordx4 v[28:29], off
	v_lshl_add_u64 v[28:29], s[18:19], 0, v[140:141]
	s_add_i32 m0, s43, 0x1e000
	v_readlane_b32 s18, v255, 43
	global_load_lds_dwordx4 v[28:29], off
	s_mulk_i32 s18, 0x4200
	s_mov_b32 s19, s13
	v_lshl_add_u64 v[142:143], s[18:19], 3, v[130:131]
	s_mov_b64 s[18:19], 0x31000
	v_or_b32_e32 v155, s41, v154
	v_lshl_add_u64 v[142:143], v[142:143], 0, s[18:19]
	v_lshlrev_b32_e32 v144, 6, v155
	s_movk_i32 s18, 0x3c0
	v_lshlrev_b32_e32 v145, 2, v155
	v_and_or_b32 v144, v144, s18, v180
	v_and_b32_e32 v145, 32, v145
	v_bitop3_b32 v162, v144, s23, v145 bitop3:0xde
	v_lshlrev_b32_e32 v145, 2, v154
	v_lshl_or_b32 v144, v154, 6, v180
	v_and_b32_e32 v145, 32, v145
	v_bitop3_b32 v156, v144, s24, v145 bitop3:0xde
	s_movk_i32 s24, 0x1580
	v_lshrrev_b32_e32 v145, 1, v148
	v_mul_lo_u32 v144, v150, s24
	s_mov_b32 s25, 0x15800
	s_cmpk_lt_u32 s22, 0x100
	v_mad_u64_u32 v[144:145], s[22:23], v145, s25, v[144:145]
	v_lshrrev_b32_e32 v147, 1, v157
	v_mul_lo_u32 v146, v159, s24
	v_or_b32_e32 v144, v144, v149
	v_mad_u64_u32 v[146:147], s[22:23], v147, s25, v[146:147]
	s_waitcnt vmcnt(6)
	v_add_lshl_u32 v180, v144, v151, 1
	s_mov_b64 s[30:31], 0x158080
	v_or_b32_e32 v146, v146, v158
	v_lshlrev_b32_e32 v161, 3, v153
	v_lshl_add_u64 v[144:145], v[180:181], 0, s[30:31]
	v_add_lshl_u32 v180, v146, v160, 1
	v_lshlrev_b32_e32 v126, 16, v64
	v_and_b32_e32 v127, 0xffff0000, v64
	v_lshlrev_b32_e32 v128, 16, v65
	v_and_b32_e32 v129, 0xffff0000, v65
	v_lshlrev_b32_e32 v114, 16, v66
	v_and_b32_e32 v115, 0xffff0000, v66
	v_lshlrev_b32_e32 v116, 16, v67
	v_and_b32_e32 v117, 0xffff0000, v67
	v_lshlrev_b32_e32 v118, 16, v60
	v_and_b32_e32 v119, 0xffff0000, v60
	v_lshlrev_b32_e32 v120, 16, v61
	v_and_b32_e32 v121, 0xffff0000, v61
	v_lshlrev_b32_e32 v122, 16, v62
	v_and_b32_e32 v123, 0xffff0000, v62
	v_lshlrev_b32_e32 v124, 16, v63
	v_and_b32_e32 v125, 0xffff0000, v63
	v_lshlrev_b32_e32 v106, 16, v56
	v_and_b32_e32 v107, 0xffff0000, v56
	v_lshlrev_b32_e32 v108, 16, v57
	v_and_b32_e32 v109, 0xffff0000, v57
	v_lshlrev_b32_e32 v98, 16, v58
	v_and_b32_e32 v99, 0xffff0000, v58
	v_lshlrev_b32_e32 v100, 16, v59
	v_and_b32_e32 v101, 0xffff0000, v59
	v_lshlrev_b32_e32 v102, 16, v52
	v_and_b32_e32 v103, 0xffff0000, v52
	v_lshlrev_b32_e32 v104, 16, v53
	v_and_b32_e32 v105, 0xffff0000, v53
	v_lshlrev_b32_e32 v110, 16, v54
	v_and_b32_e32 v111, 0xffff0000, v54
	v_lshlrev_b32_e32 v112, 16, v55
	v_and_b32_e32 v113, 0xffff0000, v55
	v_lshlrev_b32_e32 v82, 16, v50
	v_and_b32_e32 v83, 0xffff0000, v50
	v_lshlrev_b32_e32 v84, 16, v51
	v_and_b32_e32 v85, 0xffff0000, v51
	v_lshlrev_b32_e32 v86, 16, v44
	v_and_b32_e32 v87, 0xffff0000, v44
	v_lshlrev_b32_e32 v88, 16, v45
	v_and_b32_e32 v89, 0xffff0000, v45
	v_lshlrev_b32_e32 v74, 16, v40
	v_and_b32_e32 v75, 0xffff0000, v40
	v_lshlrev_b32_e32 v76, 16, v41
	v_and_b32_e32 v77, 0xffff0000, v41
	v_lshlrev_b32_e32 v54, 16, v42
	v_and_b32_e32 v55, 0xffff0000, v42
	v_lshlrev_b32_e32 v56, 16, v43
	v_and_b32_e32 v57, 0xffff0000, v43
	v_lshlrev_b32_e32 v70, 16, v36
	v_and_b32_e32 v71, 0xffff0000, v36
	v_lshlrev_b32_e32 v72, 16, v37
	v_and_b32_e32 v73, 0xffff0000, v37
	v_lshlrev_b32_e32 v78, 16, v38
	v_and_b32_e32 v79, 0xffff0000, v38
	v_lshlrev_b32_e32 v80, 16, v39
	v_and_b32_e32 v81, 0xffff0000, v39
	v_lshlrev_b32_e32 v50, 16, v32
	v_and_b32_e32 v51, 0xffff0000, v32
	v_lshlrev_b32_e32 v52, 16, v33
	v_and_b32_e32 v53, 0xffff0000, v33
	v_lshlrev_b32_e32 v38, 16, v34
	v_and_b32_e32 v39, 0xffff0000, v34
	v_lshlrev_b32_e32 v40, 16, v35
	v_and_b32_e32 v41, 0xffff0000, v35
	v_lshlrev_b32_e32 v58, 16, v30
	v_and_b32_e32 v59, 0xffff0000, v30
	v_lshlrev_b32_e32 v60, 16, v31
	v_and_b32_e32 v61, 0xffff0000, v31
	v_lshlrev_b32_e32 v22, 16, v24
	v_and_b32_e32 v23, 0xffff0000, v24
	v_lshlrev_b32_e32 v24, 16, v25
	v_and_b32_e32 v25, 0xffff0000, v25
	v_lshlrev_b32_e32 v42, 16, v26
	v_and_b32_e32 v43, 0xffff0000, v26
	v_lshlrev_b32_e32 v44, 16, v27
	v_and_b32_e32 v45, 0xffff0000, v27
	v_lshlrev_b32_e32 v62, 16, v18
	v_and_b32_e32 v63, 0xffff0000, v18
	v_lshlrev_b32_e32 v64, 16, v19
	v_and_b32_e32 v65, 0xffff0000, v19
	v_lshlrev_b32_e32 v66, 16, v20
	v_and_b32_e32 v67, 0xffff0000, v20
	v_lshlrev_b32_e32 v68, 16, v21
	v_and_b32_e32 v69, 0xffff0000, v21
	v_lshlrev_b32_e32 v30, 16, v10
	v_and_b32_e32 v31, 0xffff0000, v10
	v_lshlrev_b32_e32 v32, 16, v11
	v_and_b32_e32 v33, 0xffff0000, v11
	v_lshlrev_b32_e32 v18, 16, v12
	v_and_b32_e32 v19, 0xffff0000, v12
	v_lshlrev_b32_e32 v20, 16, v13
	v_and_b32_e32 v21, 0xffff0000, v13
	v_lshlrev_b32_e32 v26, 16, v6
	v_and_b32_e32 v27, 0xffff0000, v6
	v_lshlrev_b32_e32 v28, 16, v7
	v_and_b32_e32 v29, 0xffff0000, v7
	v_lshlrev_b32_e32 v34, 16, v8
	v_and_b32_e32 v35, 0xffff0000, v8
	v_lshlrev_b32_e32 v36, 16, v9
	v_and_b32_e32 v37, 0xffff0000, v9
	v_lshlrev_b32_e32 v10, 16, v2
	v_and_b32_e32 v11, 0xffff0000, v2
	v_lshlrev_b32_e32 v12, 16, v3
	v_and_b32_e32 v13, 0xffff0000, v3
	v_lshlrev_b32_e32 v2, 16, v4
	v_and_b32_e32 v3, 0xffff0000, v4
	v_lshlrev_b32_e32 v4, 16, v5
	v_and_b32_e32 v5, 0xffff0000, v5
	v_lshlrev_b32_e32 v6, 16, v14
	v_and_b32_e32 v7, 0xffff0000, v14
	v_lshlrev_b32_e32 v8, 16, v15
	v_and_b32_e32 v9, 0xffff0000, v15
	v_lshlrev_b32_e32 v14, 16, v16
	v_and_b32_e32 v15, 0xffff0000, v16
	v_lshlrev_b32_e32 v16, 16, v17
	v_and_b32_e32 v17, 0xffff0000, v17
	s_cselect_b64 s[18:19], -1, 0
	v_lshl_add_u64 v[146:147], v[180:181], 0, s[30:31]
	s_mov_b32 s50, 0
	v_add_u32_e32 v157, 0, v162
	v_lshlrev_b32_e32 v180, 1, v161
	s_barrier
	s_branch .LBB0_2230

.LBB0_2279:
	s_waitcnt vmcnt(8)
	v_lshlrev_b32_e32 v106, 16, v50
	v_and_b32_e32 v107, 0xffff0000, v50
	v_lshlrev_b32_e32 v108, 16, v51
	v_and_b32_e32 v109, 0xffff0000, v51
	v_lshlrev_b32_e32 v110, 16, v52
	v_and_b32_e32 v111, 0xffff0000, v52
	v_lshlrev_b32_e32 v112, 16, v53
	v_and_b32_e32 v113, 0xffff0000, v53
	v_lshlrev_b32_e32 v50, 16, v12
	v_and_b32_e32 v51, 0xffff0000, v12
	v_lshlrev_b32_e32 v52, 16, v13
	v_and_b32_e32 v53, 0xffff0000, v13
	s_add_i32 m0, s56, 0x18000
	v_lshl_add_u64 v[12:13], v[80:81], 0, s[16:17]
	s_lshl_b32 s25, s22, 13
	s_lshl_b32 s26, s55, 7
	s_waitcnt vmcnt(2)
	s_barrier
	global_load_lds_dwordx4 v[12:13], off
	v_lshl_add_u64 v[12:13], v[78:79], 0, s[16:17]
	s_add_i32 m0, s56, 0x1a000
	s_add_i32 s60, s56, 0x8000
	s_add_i32 s61, s56, 0xa000
	global_load_lds_dwordx4 v[12:13], off
	v_lshl_add_u64 v[12:13], v[66:67], 0, s[16:17]
	s_mov_b32 m0, s60
	s_add_u32 s22, s30, 0x158080
	global_load_lds_dwordx4 v[12:13], off
	v_lshl_add_u64 v[12:13], v[68:69], 0, s[16:17]
	s_mov_b32 m0, s61
	s_addc_u32 s23, s31, 0
	global_load_lds_dwordx4 v[12:13], off
	s_add_i32 m0, s56, 0x1c000
	v_lshl_add_u64 v[12:13], s[22:23], 0, v[150:151]
	global_load_lds_dwordx4 v[12:13], off
	v_lshl_add_u64 v[12:13], s[22:23], 0, v[154:155]
	s_add_i32 m0, s56, 0x1e000
	s_mov_b64 s[22:23], 0x94000
	global_load_lds_dwordx4 v[12:13], off
	v_lshl_add_u64 v[156:157], v[130:131], 0, s[22:23]
	s_mov_b64 s[22:23], 0x9000
	v_or_b32_e32 v199, s54, v197
	v_lshl_add_u64 v[158:159], v[130:131], 0, s[22:23]
	v_lshlrev_b32_e32 v130, 6, v199
	s_movk_i32 s22, 0x3c0
	v_lshlrev_b32_e32 v131, 2, v199
	v_and_or_b32 v130, v130, s22, v180
	v_and_b32_e32 v131, 32, v131
	v_bitop3_b32 v141, v130, s25, v131 bitop3:0xde
	v_lshlrev_b32_e32 v131, 2, v197
	v_lshl_or_b32 v130, v197, 6, v180
	v_and_b32_e32 v131, 32, v131
	v_bitop3_b32 v200, v130, s26, v131 bitop3:0xde
	s_movk_i32 s26, 0x1580
	v_lshrrev_b32_e32 v131, 1, v132
	v_mul_lo_u32 v130, v134, s26
	s_mov_b32 s27, 0x15800
	s_cmpk_lt_u32 s24, 0x100
	v_mad_u64_u32 v[130:131], s[24:25], v131, s27, v[130:131]
	v_or_b32_e32 v130, v130, v133
	v_add_lshl_u32 v180, v130, v135, 1
	v_lshrrev_b32_e32 v131, 1, v136
	v_mul_lo_u32 v130, v138, s26
	v_mad_u64_u32 v[130:131], s[24:25], v131, s27, v[130:131]
	s_waitcnt vmcnt(6)
	s_mov_b64 s[34:35], 0x158080
	v_or_b32_e32 v130, v130, v137
	v_lshlrev_b32_e32 v140, 3, v198
	v_lshl_add_u64 v[160:161], v[180:181], 0, s[34:35]
	v_add_lshl_u32 v180, v130, v139, 1
	v_lshlrev_b32_e32 v118, 16, v62
	v_and_b32_e32 v119, 0xffff0000, v62
	v_lshlrev_b32_e32 v120, 16, v63
	v_and_b32_e32 v121, 0xffff0000, v63
	v_lshlrev_b32_e32 v114, 16, v64
	v_and_b32_e32 v115, 0xffff0000, v64
	v_lshlrev_b32_e32 v116, 16, v65
	v_and_b32_e32 v117, 0xffff0000, v65
	v_lshlrev_b32_e32 v126, 16, v58
	v_and_b32_e32 v127, 0xffff0000, v58
	v_lshlrev_b32_e32 v128, 16, v59
	v_and_b32_e32 v129, 0xffff0000, v59
	v_lshlrev_b32_e32 v122, 16, v60
	v_and_b32_e32 v123, 0xffff0000, v60
	v_lshlrev_b32_e32 v124, 16, v61
	v_and_b32_e32 v125, 0xffff0000, v61
	v_lshlrev_b32_e32 v98, 16, v54
	v_and_b32_e32 v99, 0xffff0000, v54
	v_lshlrev_b32_e32 v100, 16, v55
	v_and_b32_e32 v101, 0xffff0000, v55
	v_lshlrev_b32_e32 v102, 16, v56
	v_and_b32_e32 v103, 0xffff0000, v56
	v_lshlrev_b32_e32 v104, 16, v57
	v_and_b32_e32 v105, 0xffff0000, v57
	v_lshlrev_b32_e32 v70, 16, v46
	v_and_b32_e32 v71, 0xffff0000, v46
	v_lshlrev_b32_e32 v72, 16, v47
	v_and_b32_e32 v73, 0xffff0000, v47
	v_lshlrev_b32_e32 v74, 16, v48
	v_and_b32_e32 v75, 0xffff0000, v48
	v_lshlrev_b32_e32 v76, 16, v49
	v_and_b32_e32 v77, 0xffff0000, v49
	v_lshlrev_b32_e32 v82, 16, v30
	v_and_b32_e32 v83, 0xffff0000, v30
	v_lshlrev_b32_e32 v84, 16, v31
	v_and_b32_e32 v85, 0xffff0000, v31
	v_lshlrev_b32_e32 v86, 16, v32
	v_and_b32_e32 v87, 0xffff0000, v32
	v_lshlrev_b32_e32 v88, 16, v33
	v_and_b32_e32 v89, 0xffff0000, v33
	v_lshlrev_b32_e32 v30, 16, v34
	v_and_b32_e32 v31, 0xffff0000, v34
	v_lshlrev_b32_e32 v32, 16, v35
	v_and_b32_e32 v33, 0xffff0000, v35
	v_lshlrev_b32_e32 v34, 16, v36
	v_and_b32_e32 v35, 0xffff0000, v36
	v_lshlrev_b32_e32 v36, 16, v37
	v_and_b32_e32 v37, 0xffff0000, v37
	v_lshlrev_b32_e32 v54, 16, v22
	v_and_b32_e32 v55, 0xffff0000, v22
	v_lshlrev_b32_e32 v56, 16, v23
	v_and_b32_e32 v57, 0xffff0000, v23
	v_lshlrev_b32_e32 v58, 16, v24
	v_and_b32_e32 v59, 0xffff0000, v24
	v_lshlrev_b32_e32 v60, 16, v25
	v_and_b32_e32 v61, 0xffff0000, v25
	v_lshlrev_b32_e32 v22, 16, v26
	v_and_b32_e32 v23, 0xffff0000, v26
	v_lshlrev_b32_e32 v24, 16, v27
	v_and_b32_e32 v25, 0xffff0000, v27
	v_lshlrev_b32_e32 v26, 16, v28
	v_and_b32_e32 v27, 0xffff0000, v28
	v_lshlrev_b32_e32 v28, 16, v29
	v_and_b32_e32 v29, 0xffff0000, v29
	v_lshlrev_b32_e32 v46, 16, v10
	v_and_b32_e32 v47, 0xffff0000, v10
	v_lshlrev_b32_e32 v48, 16, v11
	v_and_b32_e32 v49, 0xffff0000, v11
	v_lshlrev_b32_e32 v10, 16, v42
	v_and_b32_e32 v11, 0xffff0000, v42
	v_lshlrev_b32_e32 v12, 16, v43
	v_and_b32_e32 v13, 0xffff0000, v43
	v_lshlrev_b32_e32 v78, 16, v44
	v_and_b32_e32 v79, 0xffff0000, v44
	v_lshlrev_b32_e32 v80, 16, v45
	v_and_b32_e32 v81, 0xffff0000, v45
	v_lshlrev_b32_e32 v90, 16, v38
	v_and_b32_e32 v91, 0xffff0000, v38
	v_lshlrev_b32_e32 v92, 16, v39
	v_and_b32_e32 v93, 0xffff0000, v39
	v_lshlrev_b32_e32 v94, 16, v40
	v_and_b32_e32 v95, 0xffff0000, v40
	v_lshlrev_b32_e32 v96, 16, v41
	v_and_b32_e32 v97, 0xffff0000, v41
	v_lshlrev_b32_e32 v38, 16, v14
	v_and_b32_e32 v39, 0xffff0000, v14
	v_lshlrev_b32_e32 v40, 16, v15
	v_and_b32_e32 v41, 0xffff0000, v15
	v_lshlrev_b32_e32 v42, 16, v16
	v_and_b32_e32 v43, 0xffff0000, v16
	v_lshlrev_b32_e32 v44, 16, v17
	v_and_b32_e32 v45, 0xffff0000, v17
	v_lshlrev_b32_e32 v62, 16, v2
	v_and_b32_e32 v63, 0xffff0000, v2
	v_lshlrev_b32_e32 v64, 16, v3
	v_and_b32_e32 v65, 0xffff0000, v3
	v_lshlrev_b32_e32 v66, 16, v4
	v_and_b32_e32 v67, 0xffff0000, v4
	v_lshlrev_b32_e32 v68, 16, v5
	v_and_b32_e32 v69, 0xffff0000, v5
	v_lshlrev_b32_e32 v2, 16, v6
	v_and_b32_e32 v3, 0xffff0000, v6
	v_lshlrev_b32_e32 v4, 16, v7
	v_and_b32_e32 v5, 0xffff0000, v7
	v_lshlrev_b32_e32 v6, 16, v8
	v_and_b32_e32 v7, 0xffff0000, v8
	v_lshlrev_b32_e32 v8, 16, v9
	v_and_b32_e32 v9, 0xffff0000, v9
	v_lshlrev_b32_e32 v14, 16, v18
	v_and_b32_e32 v15, 0xffff0000, v18
	v_lshlrev_b32_e32 v16, 16, v19
	v_and_b32_e32 v17, 0xffff0000, v19
	v_lshlrev_b32_e32 v18, 16, v20
	v_and_b32_e32 v19, 0xffff0000, v20
	v_lshlrev_b32_e32 v20, 16, v21
	v_and_b32_e32 v21, 0xffff0000, v21
	s_cselect_b64 s[22:23], -1, 0
	v_lshl_add_u64 v[162:163], v[180:181], 0, s[34:35]
	s_mov_b32 s62, 0
	v_add_u32_e32 v201, 0, v141
	v_lshlrev_b32_e32 v180, 1, v140
	s_barrier
	s_branch .LBB0_2282
